# diff-attention next-K LDS stores spread one per PV MFMA (4..7) instead of two groups of two
# baseline (speedup 1.0000x reference)
; #define MFMA(a, b, c) __builtin_amdgcn_mfma_f32_32x32x16_bf16((a), (b), (c), 0, 0, 0)
; DI void softmax_pv(f32x16 (&sa)[2], f32x16 (&O)[4], float& m, float& l, const char* sV, int lr, int lh, bool first) {
;     ...
;   for (int i = 0; i < 16; ++i) {
;     float p0 = __builtin_amdgcn_exp2f(sa[0][i]);
;     float p1 = __builtin_amdgcn_exp2f(sa[1][i]);
;     sa[0][i] = p0;
;     sa[1][i] = p1;
;     rsum0 += p0;
;     rsum1 += p1;
;   }
;   l += rsum0 + rsum1;
;   bf16x8 pf[4];
; #pragma unroll
;   for (int g4 = 0; g4 < 4; ++g4) {
;     const int kb = g4 >> 1, s2 = g4 & 1;
;     u32x4 pp;
; #pragma unroll
;     for (int j = 0; j < 4; ++j) pp[j] = pk2(sa[kb][8 * s2 + 2 * j], sa[kb][8 * s2 + 2 * j + 1]);
;     pf[g4] = __builtin_bit_cast(bf16x8, pp);
;   }
;   const char* vrd = sV + lr * 144 + lh * 16;
;   bf16x8 vfr[4];
; #pragma unroll
;   for (int t = 0; t < 3; ++t) vfr[t] = *(const bf16x8*)(vrd + (t & 3) * (32 * 144) + (t >> 2) * 32);
;   __builtin_amdgcn_sched_group_barrier(0x100, 3, 0);
; #pragma unroll
;   for (int t = 0; t < 16; ++t) {
;     if (t + 3 < 16) {
;       vfr[(t + 3) & 3] = *(const bf16x8*)(vrd + ((t + 3) & 3) * (32 * 144) + ((t + 3) >> 2) * 32);
;       __builtin_amdgcn_sched_group_barrier(0x100, 1, 0);
;     }
;     O[t & 3] = MFMA(vfr[t & 3], pf[t >> 2], O[t & 3]);
;     __builtin_amdgcn_sched_group_barrier(0x008, 1, 0);
;   }
; DI void diff_item(const Params& p, const GroupP& g, int l_layer, int item, char* smem, bool dry) {
;     ...
;   auto storeK = [&]() {
; #pragma unroll
;     for (int i = 0; i < 4; ++i) *(u32x4*)(sK_st + i * (16 * 272)) = rk[i];
;   };
.Lpvd0_novl:
	v_exp_f32_e32 v180, v72
	v_exp_f32_e32 v181, v73
	v_exp_f32_e32 v182, v74
	v_exp_f32_e32 v183, v75
	v_cvt_pk_bf16_f32 v72, v88, v89
	v_cvt_pk_bf16_f32 v73, v90, v91
	s_waitcnt lgkmcnt(3)
	v_mfma_f32_32x32x16_bf16 v[16:31], v[202:205], v[188:191], v[16:31]
	ds_read_b128 v[202:205], v165 offset:26656
	v_cvt_pk_bf16_f32 v74, v92, v93
	v_cvt_pk_bf16_f32 v75, v94, v95
	v_exp_f32_e32 v172, v64
	v_exp_f32_e32 v173, v65
	v_exp_f32_e32 v174, v66
	v_exp_f32_e32 v175, v67
	s_waitcnt lgkmcnt(3)
	v_mfma_f32_32x32x16_bf16 v[0:15], v[206:209], v[188:191], v[0:15]
	ds_read_b128 v[188:191], v165 offset:31264
	v_exp_f32_e32 v176, v68
	v_exp_f32_e32 v177, v69
	v_exp_f32_e32 v178, v70
	v_exp_f32_e32 v179, v71
	v_cvt_pk_bf16_f32 v68, v172, v173
	v_cvt_pk_bf16_f32 v69, v174, v175
	s_waitcnt lgkmcnt(3)
	v_mfma_f32_32x32x16_bf16 v[48:63], v[192:195], v[72:75], v[48:63]
	ds_read_b128 v[192:195], v165 offset:17472
	s_waitcnt vmcnt(5)
	ds_write_b128 v145, v[116:119]
	v_cvt_pk_bf16_f32 v70, v176, v177
	v_cvt_pk_bf16_f32 v71, v178, v179
	v_exp_f32_e32 v76, v76
	v_exp_f32_e32 v77, v77
	v_exp_f32_e32 v78, v78
	v_exp_f32_e32 v79, v79
	s_waitcnt lgkmcnt(4)
	v_mfma_f32_32x32x16_bf16 v[32:47], v[196:199], v[72:75], v[32:47]
	ds_read_b128 v[196:199], v165 offset:22080
	ds_write_b128 v145, v[112:115] offset:4352
	v_cvt_pk_bf16_f32 v64, v180, v181
	v_cvt_pk_bf16_f32 v65, v182, v183
	v_cvt_pk_bf16_f32 v66, v76, v77
	v_cvt_pk_bf16_f32 v67, v78, v79
	s_and_b64 vcc, exec, s[8:9]
	s_waitcnt lgkmcnt(5)
	v_mfma_f32_32x32x16_bf16 v[16:31], v[202:205], v[72:75], v[16:31]
	ds_read_b128 v[202:205], v165 offset:26688
	ds_write_b128 v145, v[136:139] offset:8704
	s_waitcnt lgkmcnt(6)
	v_mfma_f32_32x32x16_bf16 v[0:15], v[188:191], v[72:75], v[0:15]
	ds_read_b128 v[72:75], v165 offset:31296
	s_waitcnt vmcnt(4)
	ds_write_b128 v145, v[140:143] offset:13056
	s_waitcnt lgkmcnt(7)
	v_mfma_f32_32x32x16_bf16 v[48:63], v[192:195], v[68:71], v[48:63]
	ds_read_b128 v[188:191], v165 offset:17504
	s_waitcnt lgkmcnt(6)
	v_mfma_f32_32x32x16_bf16 v[32:47], v[196:199], v[68:71], v[32:47]
	ds_read_b128 v[192:195], v165 offset:22112
	s_waitcnt lgkmcnt(5)
	v_mfma_f32_32x32x16_bf16 v[16:31], v[202:205], v[68:71], v[16:31]
	ds_read_b128 v[196:199], v165 offset:26720
	s_waitcnt lgkmcnt(4)
	v_mfma_f32_32x32x16_bf16 v[0:15], v[72:75], v[68:71], v[0:15]
	ds_read_b128 v[68:71], v165 offset:31328
	s_waitcnt lgkmcnt(0)
	s_barrier
	v_mfma_f32_32x32x16_bf16 v[48:63], v[188:191], v[64:67], v[48:63]
	v_mfma_f32_32x32x16_bf16 v[32:47], v[192:195], v[64:67], v[32:47]
	v_mfma_f32_32x32x16_bf16 v[16:31], v[196:199], v[64:67], v[16:31]
	v_mfma_f32_32x32x16_bf16 v[0:15], v[68:71], v[64:67], v[0:15]
	s_branch .LBB0_121
